# stack: P2 q-tile loads before the gate arithmetic + vT block-0 fragments fetched before the k pass + GEMM matrix-segment barrier signalled 2 MFMAs early
# baseline (speedup 1.0000x reference)
.LBB0_268:
	s_lshl_b32 s46, s46, 3
	s_ashr_i32 s47, s46, 31
	s_lshl_b64 s[46:47], s[46:47], 11
	s_lshl_b32 s0, s45, 9
	s_add_u32 s0, s0, s59
	s_addc_u32 s45, 0, s60
	v_mov_b32_e32 v234, v62
	s_add_u32 s0, s0, s46
	s_addc_u32 s45, s45, s47
	v_and_b32_e32 v235, 15, v234
	v_or_b32_e32 v2, s0, v235
	v_mov_b32_e32 v3, s45
	v_bfe_u32 v214, v234, 4, 2
	v_lshlrev_b64 v[2:3], 6, v[2:3]
	v_lshrrev_b32_e32 v12, 4, v234
	v_lshl_add_u64 v[2:3], s[12:13], 0, v[2:3]
	v_lshlrev_b32_e32 v64, 4, v214
	v_bitop3_b32 v12, v12, v235, 3 bitop3:0x6c
	v_lshl_add_u64 v[2:3], v[2:3], 0, v[64:65]
	v_lshlrev_b32_e32 v64, 9, v235
	v_lshlrev_b32_e32 v12, 4, v12
	v_add3_u32 v60, 0, v12, v64
	ds_read_b128 v[12:15], v60
	ds_read_b128 v[16:19], v60 offset:8192
	ds_read_b128 v[52:55], v60 offset:16384
	ds_read_b128 v[56:59], v60 offset:24576
	ds_read_b128 v[126:129], v60 offset:32768
	ds_read_b128 v[130:133], v60 offset:40960
	ds_read_b128 v[158:161], v60 offset:49152
	ds_read_b128 v[162:165], v60 offset:57344
	v_add_co_u32_e32 v60, vcc, s69, v2
	s_waitcnt lgkmcnt(7)
	v_mfma_f32_16x16x32_bf16 v[20:23], v[12:15], v[236:239], 0
	v_addc_co_u32_e32 v61, vcc, 0, v3, vcc
	global_load_dwordx4 v[178:181], v[60:61], off
	global_load_dwordx4 v[182:185], v[60:61], off offset:1024
	global_load_dwordx4 v[186:189], v[60:61], off offset:2048
	global_load_dwordx4 v[190:193], v[60:61], off offset:3072
	s_waitcnt vmcnt(6)
	v_mfma_f32_16x16x32_bf16 v[28:31], v[12:15], v[240:243], 0
	s_waitcnt vmcnt(5)
	v_mfma_f32_16x16x32_bf16 v[36:39], v[12:15], v[244:247], 0
	s_waitcnt vmcnt(4)
	v_mfma_f32_16x16x32_bf16 v[12:15], v[12:15], v[248:251], 0
	s_waitcnt lgkmcnt(6)
	v_mfma_f32_16x16x32_bf16 v[40:43], v[16:19], v[236:239], 0
	v_mfma_f32_16x16x32_bf16 v[44:47], v[16:19], v[240:243], 0
	v_mfma_f32_16x16x32_bf16 v[48:51], v[16:19], v[244:247], 0
	v_mfma_f32_16x16x32_bf16 v[16:19], v[16:19], v[248:251], 0
	s_waitcnt lgkmcnt(5)
	v_mfma_f32_16x16x32_bf16 v[72:75], v[52:55], v[236:239], 0
	v_mfma_f32_16x16x32_bf16 v[76:79], v[52:55], v[240:243], 0
	v_mfma_f32_16x16x32_bf16 v[80:83], v[52:55], v[244:247], 0
	v_mfma_f32_16x16x32_bf16 v[52:55], v[52:55], v[248:251], 0
	s_waitcnt lgkmcnt(4)
	v_mfma_f32_16x16x32_bf16 v[114:117], v[56:59], v[236:239], 0
	v_mfma_f32_16x16x32_bf16 v[118:121], v[56:59], v[240:243], 0
	v_mfma_f32_16x16x32_bf16 v[122:125], v[56:59], v[244:247], 0
	v_mfma_f32_16x16x32_bf16 v[56:59], v[56:59], v[248:251], 0
	s_waitcnt lgkmcnt(3)
	v_mfma_f32_16x16x32_bf16 v[134:137], v[126:129], v[236:239], 0
	v_mfma_f32_16x16x32_bf16 v[138:141], v[126:129], v[240:243], 0
	v_mfma_f32_16x16x32_bf16 v[142:145], v[126:129], v[244:247], 0
	v_mfma_f32_16x16x32_bf16 v[126:129], v[126:129], v[248:251], 0
	s_waitcnt lgkmcnt(2)
	v_mfma_f32_16x16x32_bf16 v[146:149], v[130:133], v[236:239], 0
	v_mfma_f32_16x16x32_bf16 v[150:153], v[130:133], v[240:243], 0
	v_mfma_f32_16x16x32_bf16 v[154:157], v[130:133], v[244:247], 0
	v_mfma_f32_16x16x32_bf16 v[130:133], v[130:133], v[248:251], 0
	s_waitcnt lgkmcnt(1)
	v_mfma_f32_16x16x32_bf16 v[166:169], v[158:161], v[236:239], 0
	v_mfma_f32_16x16x32_bf16 v[170:173], v[158:161], v[240:243], 0
	v_mfma_f32_16x16x32_bf16 v[174:177], v[158:161], v[244:247], 0
	v_mfma_f32_16x16x32_bf16 v[158:161], v[158:161], v[248:251], 0
	s_waitcnt lgkmcnt(0)
	v_mfma_f32_16x16x32_bf16 v[4:7], v[162:165], v[236:239], 0
	v_mfma_f32_16x16x32_bf16 v[8:11], v[162:165], v[240:243], 0
	v_mfma_f32_16x16x32_bf16 v[24:27], v[162:165], v[244:247], 0
	v_mfma_f32_16x16x32_bf16 v[32:35], v[162:165], v[248:251], 0
	v_add_co_u32_e32 v60, vcc, s70, v2
	s_nop 1
	v_addc_co_u32_e32 v61, vcc, 0, v3, vcc
	global_load_dwordx4 v[162:165], v[60:61], off
	global_load_dwordx4 v[194:197], v[60:61], off offset:1024
	global_load_dwordx4 v[198:201], v[60:61], off offset:2048
	global_load_dwordx4 v[202:205], v[60:61], off offset:3072
	v_bitop3_b32 v60, v214, v235, 4 bitop3:0x36
	v_lshlrev_b32_e32 v60, 4, v60
	v_add3_u32 v60, 0, v60, v64
	ds_read_b128 v[206:209], v60
	ds_read_b128 v[210:213], v60 offset:8192
	s_waitcnt vmcnt(7) lgkmcnt(1)
	v_mfma_f32_16x16x32_bf16 v[20:23], v[206:209], v[178:181], v[20:23]
	s_waitcnt vmcnt(6)
	v_mfma_f32_16x16x32_bf16 v[28:31], v[206:209], v[182:185], v[28:31]
	s_waitcnt vmcnt(5)
	v_mfma_f32_16x16x32_bf16 v[36:39], v[206:209], v[186:189], v[36:39]
	s_waitcnt vmcnt(4)
	v_mfma_f32_16x16x32_bf16 v[12:15], v[206:209], v[190:193], v[12:15]
	s_waitcnt lgkmcnt(0)
	v_mfma_f32_16x16x32_bf16 v[40:43], v[210:213], v[178:181], v[40:43]
	v_mfma_f32_16x16x32_bf16 v[44:47], v[210:213], v[182:185], v[44:47]
	v_mfma_f32_16x16x32_bf16 v[48:51], v[210:213], v[186:189], v[48:51]
	v_mfma_f32_16x16x32_bf16 v[16:19], v[210:213], v[190:193], v[16:19]
	ds_read_b128 v[206:209], v60 offset:16384
	ds_read_b128 v[210:213], v60 offset:24576
	s_waitcnt lgkmcnt(1)
	v_mfma_f32_16x16x32_bf16 v[72:75], v[206:209], v[178:181], v[72:75]
	v_mfma_f32_16x16x32_bf16 v[76:79], v[206:209], v[182:185], v[76:79]
	v_mfma_f32_16x16x32_bf16 v[80:83], v[206:209], v[186:189], v[80:83]
	v_mfma_f32_16x16x32_bf16 v[52:55], v[206:209], v[190:193], v[52:55]
	s_waitcnt lgkmcnt(0)
	v_mfma_f32_16x16x32_bf16 v[114:117], v[210:213], v[178:181], v[114:117]
	v_mfma_f32_16x16x32_bf16 v[118:121], v[210:213], v[182:185], v[118:121]
	v_mfma_f32_16x16x32_bf16 v[122:125], v[210:213], v[186:189], v[122:125]
	v_mfma_f32_16x16x32_bf16 v[56:59], v[210:213], v[190:193], v[56:59]
	ds_read_b128 v[206:209], v60 offset:32768
	ds_read_b128 v[210:213], v60 offset:40960
	s_waitcnt lgkmcnt(1)
	v_mfma_f32_16x16x32_bf16 v[134:137], v[206:209], v[178:181], v[134:137]
	v_mfma_f32_16x16x32_bf16 v[138:141], v[206:209], v[182:185], v[138:141]
	v_mfma_f32_16x16x32_bf16 v[142:145], v[206:209], v[186:189], v[142:145]
	v_mfma_f32_16x16x32_bf16 v[126:129], v[206:209], v[190:193], v[126:129]
	s_waitcnt lgkmcnt(0)
	v_mfma_f32_16x16x32_bf16 v[146:149], v[210:213], v[178:181], v[146:149]
	v_mfma_f32_16x16x32_bf16 v[150:153], v[210:213], v[182:185], v[150:153]
	v_mfma_f32_16x16x32_bf16 v[154:157], v[210:213], v[186:189], v[154:157]
	v_mfma_f32_16x16x32_bf16 v[130:133], v[210:213], v[190:193], v[130:133]
	ds_read_b128 v[206:209], v60 offset:49152
	ds_read_b128 v[210:213], v60 offset:57344
	s_waitcnt lgkmcnt(1)
	v_mfma_f32_16x16x32_bf16 v[166:169], v[206:209], v[178:181], v[166:169]
	v_mfma_f32_16x16x32_bf16 v[170:173], v[206:209], v[182:185], v[170:173]
	v_mfma_f32_16x16x32_bf16 v[174:177], v[206:209], v[186:189], v[174:177]
	v_mfma_f32_16x16x32_bf16 v[158:161], v[206:209], v[190:193], v[158:161]
	s_waitcnt lgkmcnt(0)
	v_mfma_f32_16x16x32_bf16 v[4:7], v[210:213], v[178:181], v[4:7]
	v_mfma_f32_16x16x32_bf16 v[8:11], v[210:213], v[182:185], v[8:11]
	v_mfma_f32_16x16x32_bf16 v[24:27], v[210:213], v[186:189], v[24:27]
	v_mfma_f32_16x16x32_bf16 v[32:35], v[210:213], v[190:193], v[32:35]
	v_add_co_u32_e32 v60, vcc, s67, v2
	s_nop 1
	v_addc_co_u32_e32 v61, vcc, 0, v3, vcc
	global_load_dwordx4 v[178:181], v[60:61], off
	global_load_dwordx4 v[182:185], v[60:61], off offset:1024
	global_load_dwordx4 v[186:189], v[60:61], off offset:2048
	global_load_dwordx4 v[190:193], v[60:61], off offset:3072
	v_bitop3_b32 v60, v214, v235, 8 bitop3:0x36
	v_lshlrev_b32_e32 v60, 4, v60
	v_add3_u32 v60, 0, v60, v64
	ds_read_b128 v[206:209], v60
	ds_read_b128 v[210:213], v60 offset:8192
	s_waitcnt vmcnt(7) lgkmcnt(1)
	v_mfma_f32_16x16x32_bf16 v[20:23], v[206:209], v[162:165], v[20:23]
	s_waitcnt vmcnt(6)
	v_mfma_f32_16x16x32_bf16 v[28:31], v[206:209], v[194:197], v[28:31]
	s_waitcnt vmcnt(5)
	v_mfma_f32_16x16x32_bf16 v[36:39], v[206:209], v[198:201], v[36:39]
	s_waitcnt vmcnt(4)
	v_mfma_f32_16x16x32_bf16 v[12:15], v[206:209], v[202:205], v[12:15]
	s_waitcnt lgkmcnt(0)
	v_mfma_f32_16x16x32_bf16 v[40:43], v[210:213], v[162:165], v[40:43]
	v_mfma_f32_16x16x32_bf16 v[44:47], v[210:213], v[194:197], v[44:47]
	v_mfma_f32_16x16x32_bf16 v[48:51], v[210:213], v[198:201], v[48:51]
	v_mfma_f32_16x16x32_bf16 v[16:19], v[210:213], v[202:205], v[16:19]
	ds_read_b128 v[206:209], v60 offset:16384
	ds_read_b128 v[210:213], v60 offset:24576
	s_waitcnt lgkmcnt(1)
	v_mfma_f32_16x16x32_bf16 v[72:75], v[206:209], v[162:165], v[72:75]
	v_mfma_f32_16x16x32_bf16 v[76:79], v[206:209], v[194:197], v[76:79]
	v_mfma_f32_16x16x32_bf16 v[80:83], v[206:209], v[198:201], v[80:83]
	v_mfma_f32_16x16x32_bf16 v[52:55], v[206:209], v[202:205], v[52:55]
	s_waitcnt lgkmcnt(0)
	v_mfma_f32_16x16x32_bf16 v[114:117], v[210:213], v[162:165], v[114:117]
	v_mfma_f32_16x16x32_bf16 v[118:121], v[210:213], v[194:197], v[118:121]
	v_mfma_f32_16x16x32_bf16 v[122:125], v[210:213], v[198:201], v[122:125]
	v_mfma_f32_16x16x32_bf16 v[56:59], v[210:213], v[202:205], v[56:59]
	ds_read_b128 v[206:209], v60 offset:32768
	ds_read_b128 v[210:213], v60 offset:40960
	s_waitcnt lgkmcnt(1)
	v_mfma_f32_16x16x32_bf16 v[134:137], v[206:209], v[162:165], v[134:137]
	v_mfma_f32_16x16x32_bf16 v[138:141], v[206:209], v[194:197], v[138:141]
	v_mfma_f32_16x16x32_bf16 v[142:145], v[206:209], v[198:201], v[142:145]
	v_mfma_f32_16x16x32_bf16 v[126:129], v[206:209], v[202:205], v[126:129]
	s_waitcnt lgkmcnt(0)
	v_mfma_f32_16x16x32_bf16 v[146:149], v[210:213], v[162:165], v[146:149]
	v_mfma_f32_16x16x32_bf16 v[150:153], v[210:213], v[194:197], v[150:153]
	v_mfma_f32_16x16x32_bf16 v[154:157], v[210:213], v[198:201], v[154:157]
	v_mfma_f32_16x16x32_bf16 v[130:133], v[210:213], v[202:205], v[130:133]
	ds_read_b128 v[206:209], v60 offset:49152
	ds_read_b128 v[210:213], v60 offset:57344
	s_waitcnt lgkmcnt(1)
	v_mfma_f32_16x16x32_bf16 v[166:169], v[206:209], v[162:165], v[166:169]
	v_mfma_f32_16x16x32_bf16 v[170:173], v[206:209], v[194:197], v[170:173]
	v_mfma_f32_16x16x32_bf16 v[174:177], v[206:209], v[198:201], v[174:177]
	v_mfma_f32_16x16x32_bf16 v[158:161], v[206:209], v[202:205], v[158:161]
	s_waitcnt lgkmcnt(0)
	v_mfma_f32_16x16x32_bf16 v[4:7], v[210:213], v[162:165], v[4:7]
	v_mfma_f32_16x16x32_bf16 v[8:11], v[210:213], v[194:197], v[8:11]
	v_mfma_f32_16x16x32_bf16 v[24:27], v[210:213], v[198:201], v[24:27]
	v_mfma_f32_16x16x32_bf16 v[32:35], v[210:213], v[202:205], v[32:35]
	v_add_co_u32_e32 v60, vcc, s71, v2
	s_nop 1
	v_addc_co_u32_e32 v61, vcc, 0, v3, vcc
	global_load_dwordx4 v[162:165], v[60:61], off
	global_load_dwordx4 v[194:197], v[60:61], off offset:1024
	global_load_dwordx4 v[198:201], v[60:61], off offset:2048
	global_load_dwordx4 v[202:205], v[60:61], off offset:3072
	v_bitop3_b32 v60, v214, v235, 12 bitop3:0x36
	v_lshlrev_b32_e32 v60, 4, v60
	v_add3_u32 v60, 0, v60, v64
	ds_read_b128 v[206:209], v60
	ds_read_b128 v[210:213], v60 offset:8192
	s_waitcnt vmcnt(7) lgkmcnt(1)
	v_mfma_f32_16x16x32_bf16 v[20:23], v[206:209], v[178:181], v[20:23]
	s_waitcnt vmcnt(6)
	v_mfma_f32_16x16x32_bf16 v[28:31], v[206:209], v[182:185], v[28:31]
	s_waitcnt vmcnt(5)
	v_mfma_f32_16x16x32_bf16 v[36:39], v[206:209], v[186:189], v[36:39]
	s_waitcnt vmcnt(4)
	v_mfma_f32_16x16x32_bf16 v[12:15], v[206:209], v[190:193], v[12:15]
	s_waitcnt lgkmcnt(0)
	v_mfma_f32_16x16x32_bf16 v[40:43], v[210:213], v[178:181], v[40:43]
	v_mfma_f32_16x16x32_bf16 v[44:47], v[210:213], v[182:185], v[44:47]
	v_mfma_f32_16x16x32_bf16 v[48:51], v[210:213], v[186:189], v[48:51]
	v_mfma_f32_16x16x32_bf16 v[16:19], v[210:213], v[190:193], v[16:19]
	ds_read_b128 v[206:209], v60 offset:16384
	ds_read_b128 v[210:213], v60 offset:24576
	s_waitcnt lgkmcnt(1)
	v_mfma_f32_16x16x32_bf16 v[72:75], v[206:209], v[178:181], v[72:75]
	v_mfma_f32_16x16x32_bf16 v[76:79], v[206:209], v[182:185], v[76:79]
	v_mfma_f32_16x16x32_bf16 v[80:83], v[206:209], v[186:189], v[80:83]
	v_mfma_f32_16x16x32_bf16 v[52:55], v[206:209], v[190:193], v[52:55]
	s_waitcnt lgkmcnt(0)
	v_mfma_f32_16x16x32_bf16 v[114:117], v[210:213], v[178:181], v[114:117]
	v_mfma_f32_16x16x32_bf16 v[118:121], v[210:213], v[182:185], v[118:121]
	v_mfma_f32_16x16x32_bf16 v[122:125], v[210:213], v[186:189], v[122:125]
	v_mfma_f32_16x16x32_bf16 v[56:59], v[210:213], v[190:193], v[56:59]
	ds_read_b128 v[206:209], v60 offset:32768
	ds_read_b128 v[210:213], v60 offset:40960
	s_waitcnt lgkmcnt(1)
	v_mfma_f32_16x16x32_bf16 v[134:137], v[206:209], v[178:181], v[134:137]
	v_mfma_f32_16x16x32_bf16 v[138:141], v[206:209], v[182:185], v[138:141]
	v_mfma_f32_16x16x32_bf16 v[142:145], v[206:209], v[186:189], v[142:145]
	v_mfma_f32_16x16x32_bf16 v[126:129], v[206:209], v[190:193], v[126:129]
	s_waitcnt lgkmcnt(0)
	v_mfma_f32_16x16x32_bf16 v[146:149], v[210:213], v[178:181], v[146:149]
	v_mfma_f32_16x16x32_bf16 v[150:153], v[210:213], v[182:185], v[150:153]
	v_mfma_f32_16x16x32_bf16 v[154:157], v[210:213], v[186:189], v[154:157]
	v_mfma_f32_16x16x32_bf16 v[130:133], v[210:213], v[190:193], v[130:133]
	ds_read_b128 v[206:209], v60 offset:49152
	ds_read_b128 v[210:213], v60 offset:57344
	s_waitcnt lgkmcnt(1)
	v_mfma_f32_16x16x32_bf16 v[166:169], v[206:209], v[178:181], v[166:169]
	v_mfma_f32_16x16x32_bf16 v[170:173], v[206:209], v[182:185], v[170:173]
	v_mfma_f32_16x16x32_bf16 v[174:177], v[206:209], v[186:189], v[174:177]
	v_mfma_f32_16x16x32_bf16 v[158:161], v[206:209], v[190:193], v[158:161]
	s_waitcnt lgkmcnt(0)
	v_mfma_f32_16x16x32_bf16 v[4:7], v[210:213], v[178:181], v[4:7]
	v_mfma_f32_16x16x32_bf16 v[8:11], v[210:213], v[182:185], v[8:11]
	v_mfma_f32_16x16x32_bf16 v[24:27], v[210:213], v[186:189], v[24:27]
	v_mfma_f32_16x16x32_bf16 v[32:35], v[210:213], v[190:193], v[32:35]
	v_add_co_u32_e32 v60, vcc, s72, v2
	s_nop 1
	v_addc_co_u32_e32 v61, vcc, 0, v3, vcc
	global_load_dwordx4 v[178:181], v[60:61], off
	global_load_dwordx4 v[182:185], v[60:61], off offset:1024
	global_load_dwordx4 v[186:189], v[60:61], off offset:2048
	global_load_dwordx4 v[190:193], v[60:61], off offset:3072
	v_bitop3_b32 v60, v214, v235, 16 bitop3:0x36
	v_lshlrev_b32_e32 v60, 4, v60
	v_add3_u32 v60, 0, v60, v64
	ds_read_b128 v[206:209], v60
	ds_read_b128 v[210:213], v60 offset:8192
	s_waitcnt vmcnt(7) lgkmcnt(1)
	v_mfma_f32_16x16x32_bf16 v[20:23], v[206:209], v[162:165], v[20:23]
	s_waitcnt vmcnt(6)
	v_mfma_f32_16x16x32_bf16 v[28:31], v[206:209], v[194:197], v[28:31]
	s_waitcnt vmcnt(5)
	v_mfma_f32_16x16x32_bf16 v[36:39], v[206:209], v[198:201], v[36:39]
	s_waitcnt vmcnt(4)
	v_mfma_f32_16x16x32_bf16 v[12:15], v[206:209], v[202:205], v[12:15]
	s_waitcnt lgkmcnt(0)
	v_mfma_f32_16x16x32_bf16 v[40:43], v[210:213], v[162:165], v[40:43]
	v_mfma_f32_16x16x32_bf16 v[44:47], v[210:213], v[194:197], v[44:47]
	v_mfma_f32_16x16x32_bf16 v[48:51], v[210:213], v[198:201], v[48:51]
	v_mfma_f32_16x16x32_bf16 v[16:19], v[210:213], v[202:205], v[16:19]
	ds_read_b128 v[206:209], v60 offset:16384
	ds_read_b128 v[210:213], v60 offset:24576
	s_waitcnt lgkmcnt(1)
	v_mfma_f32_16x16x32_bf16 v[72:75], v[206:209], v[162:165], v[72:75]
	v_mfma_f32_16x16x32_bf16 v[76:79], v[206:209], v[194:197], v[76:79]
	v_mfma_f32_16x16x32_bf16 v[80:83], v[206:209], v[198:201], v[80:83]
	v_mfma_f32_16x16x32_bf16 v[52:55], v[206:209], v[202:205], v[52:55]
	s_waitcnt lgkmcnt(0)
	v_mfma_f32_16x16x32_bf16 v[114:117], v[210:213], v[162:165], v[114:117]
	v_mfma_f32_16x16x32_bf16 v[118:121], v[210:213], v[194:197], v[118:121]
	v_mfma_f32_16x16x32_bf16 v[122:125], v[210:213], v[198:201], v[122:125]
	v_mfma_f32_16x16x32_bf16 v[56:59], v[210:213], v[202:205], v[56:59]
	ds_read_b128 v[206:209], v60 offset:32768
	ds_read_b128 v[210:213], v60 offset:40960
	s_waitcnt lgkmcnt(1)
	v_mfma_f32_16x16x32_bf16 v[134:137], v[206:209], v[162:165], v[134:137]
	v_mfma_f32_16x16x32_bf16 v[138:141], v[206:209], v[194:197], v[138:141]
	v_mfma_f32_16x16x32_bf16 v[142:145], v[206:209], v[198:201], v[142:145]
	v_mfma_f32_16x16x32_bf16 v[126:129], v[206:209], v[202:205], v[126:129]
	s_waitcnt lgkmcnt(0)
	v_mfma_f32_16x16x32_bf16 v[146:149], v[210:213], v[162:165], v[146:149]
	v_mfma_f32_16x16x32_bf16 v[150:153], v[210:213], v[194:197], v[150:153]
	v_mfma_f32_16x16x32_bf16 v[154:157], v[210:213], v[198:201], v[154:157]
	v_mfma_f32_16x16x32_bf16 v[130:133], v[210:213], v[202:205], v[130:133]
	ds_read_b128 v[206:209], v60 offset:49152
	ds_read_b128 v[210:213], v60 offset:57344
	s_waitcnt lgkmcnt(1)
	v_mfma_f32_16x16x32_bf16 v[166:169], v[206:209], v[162:165], v[166:169]
	v_mfma_f32_16x16x32_bf16 v[170:173], v[206:209], v[194:197], v[170:173]
	v_mfma_f32_16x16x32_bf16 v[174:177], v[206:209], v[198:201], v[174:177]
	v_mfma_f32_16x16x32_bf16 v[158:161], v[206:209], v[202:205], v[158:161]
	s_waitcnt lgkmcnt(0)
	v_mfma_f32_16x16x32_bf16 v[4:7], v[210:213], v[162:165], v[4:7]
	v_mfma_f32_16x16x32_bf16 v[8:11], v[210:213], v[194:197], v[8:11]
	v_mfma_f32_16x16x32_bf16 v[24:27], v[210:213], v[198:201], v[24:27]
	v_mfma_f32_16x16x32_bf16 v[32:35], v[210:213], v[202:205], v[32:35]
	v_add_co_u32_e32 v60, vcc, s68, v2
	s_nop 1
	v_addc_co_u32_e32 v61, vcc, 0, v3, vcc
	global_load_dwordx4 v[162:165], v[60:61], off
	global_load_dwordx4 v[194:197], v[60:61], off offset:1024
	global_load_dwordx4 v[198:201], v[60:61], off offset:2048
	global_load_dwordx4 v[202:205], v[60:61], off offset:3072
	v_bitop3_b32 v60, v214, v235, 20 bitop3:0x36
	v_lshlrev_b32_e32 v60, 4, v60
	v_add3_u32 v60, 0, v60, v64
	ds_read_b128 v[206:209], v60
	ds_read_b128 v[210:213], v60 offset:8192
	s_waitcnt vmcnt(7) lgkmcnt(1)
	v_mfma_f32_16x16x32_bf16 v[20:23], v[206:209], v[178:181], v[20:23]
	s_waitcnt vmcnt(6)
	v_mfma_f32_16x16x32_bf16 v[28:31], v[206:209], v[182:185], v[28:31]
	s_waitcnt vmcnt(5)
	v_mfma_f32_16x16x32_bf16 v[36:39], v[206:209], v[186:189], v[36:39]
	s_waitcnt vmcnt(4)
	v_mfma_f32_16x16x32_bf16 v[12:15], v[206:209], v[190:193], v[12:15]
	s_waitcnt lgkmcnt(0)
	v_mfma_f32_16x16x32_bf16 v[40:43], v[210:213], v[178:181], v[40:43]
	v_mfma_f32_16x16x32_bf16 v[44:47], v[210:213], v[182:185], v[44:47]
	v_mfma_f32_16x16x32_bf16 v[48:51], v[210:213], v[186:189], v[48:51]
	v_mfma_f32_16x16x32_bf16 v[16:19], v[210:213], v[190:193], v[16:19]
	ds_read_b128 v[206:209], v60 offset:16384
	ds_read_b128 v[210:213], v60 offset:24576
	s_waitcnt lgkmcnt(1)
	v_mfma_f32_16x16x32_bf16 v[72:75], v[206:209], v[178:181], v[72:75]
	v_mfma_f32_16x16x32_bf16 v[76:79], v[206:209], v[182:185], v[76:79]
	v_mfma_f32_16x16x32_bf16 v[80:83], v[206:209], v[186:189], v[80:83]
	v_mfma_f32_16x16x32_bf16 v[52:55], v[206:209], v[190:193], v[52:55]
	s_waitcnt lgkmcnt(0)
	v_mfma_f32_16x16x32_bf16 v[114:117], v[210:213], v[178:181], v[114:117]
	v_mfma_f32_16x16x32_bf16 v[118:121], v[210:213], v[182:185], v[118:121]
	v_mfma_f32_16x16x32_bf16 v[122:125], v[210:213], v[186:189], v[122:125]
	v_mfma_f32_16x16x32_bf16 v[56:59], v[210:213], v[190:193], v[56:59]
	ds_read_b128 v[206:209], v60 offset:32768
	ds_read_b128 v[210:213], v60 offset:40960
	s_waitcnt lgkmcnt(1)
	v_mfma_f32_16x16x32_bf16 v[134:137], v[206:209], v[178:181], v[134:137]
	v_mfma_f32_16x16x32_bf16 v[138:141], v[206:209], v[182:185], v[138:141]
	v_mfma_f32_16x16x32_bf16 v[142:145], v[206:209], v[186:189], v[142:145]
	v_mfma_f32_16x16x32_bf16 v[126:129], v[206:209], v[190:193], v[126:129]
	s_waitcnt lgkmcnt(0)
	v_mfma_f32_16x16x32_bf16 v[146:149], v[210:213], v[178:181], v[146:149]
	v_mfma_f32_16x16x32_bf16 v[150:153], v[210:213], v[182:185], v[150:153]
	v_mfma_f32_16x16x32_bf16 v[154:157], v[210:213], v[186:189], v[154:157]
	v_mfma_f32_16x16x32_bf16 v[130:133], v[210:213], v[190:193], v[130:133]
	ds_read_b128 v[206:209], v60 offset:49152
	ds_read_b128 v[210:213], v60 offset:57344
	s_waitcnt lgkmcnt(1)
	v_mfma_f32_16x16x32_bf16 v[166:169], v[206:209], v[178:181], v[166:169]
	v_mfma_f32_16x16x32_bf16 v[170:173], v[206:209], v[182:185], v[170:173]
	v_mfma_f32_16x16x32_bf16 v[174:177], v[206:209], v[186:189], v[174:177]
	v_mfma_f32_16x16x32_bf16 v[158:161], v[206:209], v[190:193], v[158:161]
	s_waitcnt lgkmcnt(0)
	v_mfma_f32_16x16x32_bf16 v[4:7], v[210:213], v[178:181], v[4:7]
	v_mfma_f32_16x16x32_bf16 v[8:11], v[210:213], v[182:185], v[8:11]
	v_mfma_f32_16x16x32_bf16 v[24:27], v[210:213], v[186:189], v[24:27]
	v_mfma_f32_16x16x32_bf16 v[32:35], v[210:213], v[190:193], v[32:35]
	v_add_co_u32_e32 v2, vcc, s73, v2
	s_nop 1
	v_addc_co_u32_e32 v3, vcc, 0, v3, vcc
	global_load_dwordx4 v[178:181], v[2:3], off
	global_load_dwordx4 v[182:185], v[2:3], off offset:1024
	global_load_dwordx4 v[186:189], v[2:3], off offset:2048
	global_load_dwordx4 v[190:193], v[2:3], off offset:3072
	v_bitop3_b32 v2, v214, v235, 24 bitop3:0x36
	v_lshlrev_b32_e32 v2, 4, v2
	v_add3_u32 v2, 0, v2, v64
	ds_read_b128 v[206:209], v2
	ds_read_b128 v[210:213], v2 offset:8192
	s_waitcnt vmcnt(7) lgkmcnt(1)
	v_mfma_f32_16x16x32_bf16 v[20:23], v[206:209], v[162:165], v[20:23]
	s_waitcnt vmcnt(6)
	v_mfma_f32_16x16x32_bf16 v[28:31], v[206:209], v[194:197], v[28:31]
	s_waitcnt vmcnt(5)
	v_mfma_f32_16x16x32_bf16 v[36:39], v[206:209], v[198:201], v[36:39]
	s_waitcnt vmcnt(4)
	v_mfma_f32_16x16x32_bf16 v[12:15], v[206:209], v[202:205], v[12:15]
	s_waitcnt lgkmcnt(0)
	v_mfma_f32_16x16x32_bf16 v[40:43], v[210:213], v[162:165], v[40:43]
	v_mfma_f32_16x16x32_bf16 v[44:47], v[210:213], v[194:197], v[44:47]
	v_mfma_f32_16x16x32_bf16 v[48:51], v[210:213], v[198:201], v[48:51]
	v_mfma_f32_16x16x32_bf16 v[16:19], v[210:213], v[202:205], v[16:19]
	ds_read_b128 v[206:209], v2 offset:16384
	ds_read_b128 v[210:213], v2 offset:24576
	s_waitcnt lgkmcnt(1)
	v_mfma_f32_16x16x32_bf16 v[72:75], v[206:209], v[162:165], v[72:75]
	v_mfma_f32_16x16x32_bf16 v[76:79], v[206:209], v[194:197], v[76:79]
	v_mfma_f32_16x16x32_bf16 v[80:83], v[206:209], v[198:201], v[80:83]
	v_mfma_f32_16x16x32_bf16 v[206:209], v[206:209], v[202:205], v[52:55]
	s_waitcnt lgkmcnt(0)
	v_mfma_f32_16x16x32_bf16 v[114:117], v[210:213], v[162:165], v[114:117]
	v_mfma_f32_16x16x32_bf16 v[118:121], v[210:213], v[194:197], v[118:121]
	v_mfma_f32_16x16x32_bf16 v[122:125], v[210:213], v[198:201], v[122:125]
	v_mfma_f32_16x16x32_bf16 v[210:213], v[210:213], v[202:205], v[56:59]
	ds_read_b128 v[52:55], v2 offset:32768
	s_nop 1
	ds_read_b128 v[56:59], v2 offset:40960
	s_waitcnt lgkmcnt(1)
	v_mfma_f32_16x16x32_bf16 v[134:137], v[52:55], v[162:165], v[134:137]
	v_mfma_f32_16x16x32_bf16 v[138:141], v[52:55], v[194:197], v[138:141]
	v_mfma_f32_16x16x32_bf16 v[142:145], v[52:55], v[198:201], v[142:145]
	v_mfma_f32_16x16x32_bf16 v[126:129], v[52:55], v[202:205], v[126:129]
	s_waitcnt lgkmcnt(0)
	v_mfma_f32_16x16x32_bf16 v[146:149], v[56:59], v[162:165], v[146:149]
	v_mfma_f32_16x16x32_bf16 v[150:153], v[56:59], v[194:197], v[150:153]
	v_mfma_f32_16x16x32_bf16 v[154:157], v[56:59], v[198:201], v[154:157]
	v_mfma_f32_16x16x32_bf16 v[130:133], v[56:59], v[202:205], v[130:133]
	ds_read_b128 v[52:55], v2 offset:49152
	ds_read_b128 v[56:59], v2 offset:57344
	s_waitcnt lgkmcnt(1)
	v_mfma_f32_16x16x32_bf16 v[166:169], v[52:55], v[162:165], v[166:169]
	v_mfma_f32_16x16x32_bf16 v[170:173], v[52:55], v[194:197], v[170:173]
	v_mfma_f32_16x16x32_bf16 v[174:177], v[52:55], v[198:201], v[174:177]
	v_mfma_f32_16x16x32_bf16 v[158:161], v[52:55], v[202:205], v[158:161]
	s_waitcnt lgkmcnt(0)
	v_mfma_f32_16x16x32_bf16 v[162:165], v[56:59], v[162:165], v[4:7]
	v_mfma_f32_16x16x32_bf16 v[6:9], v[56:59], v[194:197], v[8:11]
	v_mfma_f32_16x16x32_bf16 v[194:197], v[56:59], v[198:201], v[24:27]
	v_mfma_f32_16x16x32_bf16 v[198:201], v[56:59], v[202:205], v[32:35]
	v_bitop3_b32 v2, v214, v235, 28 bitop3:0x36
	v_lshlrev_b32_e32 v2, 4, v2
	v_add3_u32 v64, 0, v2, v64
	ds_read_b128 v[2:5], v64
	ds_read_b128 v[32:35], v64 offset:8192
	s_waitcnt vmcnt(3) lgkmcnt(1)
	v_mfma_f32_16x16x32_bf16 v[202:205], v[2:5], v[178:181], v[20:23]
	s_waitcnt vmcnt(2)
	v_mfma_f32_16x16x32_bf16 v[214:217], v[2:5], v[182:185], v[28:31]
	s_waitcnt vmcnt(1)
	v_mfma_f32_16x16x32_bf16 v[58:61], v[2:5], v[186:189], v[36:39]
	s_waitcnt vmcnt(0)
	v_mfma_f32_16x16x32_bf16 v[26:29], v[2:5], v[190:193], v[12:15]
	ds_read_b128 v[2:5], v64 offset:16384
	s_nop 1
	ds_read_b128 v[10:13], v64 offset:24576
	s_waitcnt lgkmcnt(2)
	v_mfma_f32_16x16x32_bf16 v[218:221], v[32:35], v[178:181], v[40:43]
	v_mfma_f32_16x16x32_bf16 v[222:225], v[32:35], v[182:185], v[44:47]
	v_mfma_f32_16x16x32_bf16 v[226:229], v[32:35], v[186:189], v[48:51]
	v_mfma_f32_16x16x32_bf16 v[30:33], v[32:35], v[190:193], v[16:19]
	s_waitcnt lgkmcnt(1)
	v_mfma_f32_16x16x32_bf16 v[230:233], v[2:5], v[178:181], v[72:75]
	v_mfma_f32_16x16x32_bf16 v[74:77], v[2:5], v[182:185], v[76:79]
	v_mfma_f32_16x16x32_bf16 v[50:53], v[2:5], v[186:189], v[80:83]
	v_mfma_f32_16x16x32_bf16 v[18:21], v[2:5], v[190:193], v[206:209]
	ds_read_b128 v[2:5], v64 offset:32768
	ds_read_b128 v[14:17], v64 offset:40960
	s_waitcnt lgkmcnt(2)
	v_mfma_f32_16x16x32_bf16 v[78:81], v[10:13], v[178:181], v[114:117]
	v_mfma_f32_16x16x32_bf16 v[114:117], v[10:13], v[182:185], v[118:121]
	v_mfma_f32_16x16x32_bf16 v[54:57], v[10:13], v[186:189], v[122:125]
	v_mfma_f32_16x16x32_bf16 v[22:25], v[10:13], v[190:193], v[210:213]
	s_waitcnt lgkmcnt(1)
	v_mfma_f32_16x16x32_bf16 v[118:121], v[2:5], v[178:181], v[134:137]
	v_mfma_f32_16x16x32_bf16 v[122:125], v[2:5], v[182:185], v[138:141]
	v_mfma_f32_16x16x32_bf16 v[42:45], v[2:5], v[186:189], v[142:145]
	v_mfma_f32_16x16x32_bf16 v[10:13], v[2:5], v[190:193], v[126:129]
	s_waitcnt lgkmcnt(0)
	v_mfma_f32_16x16x32_bf16 v[126:129], v[14:17], v[178:181], v[146:149]
	v_mfma_f32_16x16x32_bf16 v[134:137], v[14:17], v[182:185], v[150:153]
	v_mfma_f32_16x16x32_bf16 v[46:49], v[14:17], v[186:189], v[154:157]
	v_mfma_f32_16x16x32_bf16 v[14:17], v[14:17], v[190:193], v[130:133]
	ds_read_b128 v[2:5], v64 offset:49152
	s_nop 1
	ds_read_b128 v[130:133], v64 offset:57344
	s_waitcnt lgkmcnt(1)
	v_mfma_f32_16x16x32_bf16 v[138:141], v[2:5], v[178:181], v[166:169]
	v_mfma_f32_16x16x32_bf16 v[142:145], v[2:5], v[182:185], v[170:173]
	v_mfma_f32_16x16x32_bf16 v[34:37], v[2:5], v[186:189], v[174:177]
	v_mfma_f32_16x16x32_bf16 v[2:5], v[2:5], v[190:193], v[158:161]
	s_waitcnt lgkmcnt(0)
	v_mfma_f32_16x16x32_bf16 v[146:149], v[130:133], v[178:181], v[162:165]
	v_mfma_f32_16x16x32_bf16 v[150:153], v[130:133], v[182:185], v[6:9]
	v_mfma_f32_16x16x32_bf16 v[38:41], v[130:133], v[186:189], v[194:197]
	v_mfma_f32_16x16x32_bf16 v[6:9], v[130:133], v[190:193], v[198:201]
	s_ashr_i32 s45, s44, 31
	s_lshl_b64 s[46:47], s[44:45], 9
	s_add_u32 s0, s46, s59
	s_addc_u32 s45, s47, s60
	v_or_b32_e32 v72, s0, v235
	v_mov_b32_e32 v73, s45
	v_lshlrev_b64 v[72:73], 8, v[72:73]
	v_and_b32_e32 v64, 16, v234
	v_lshl_add_u64 v[72:73], s[20:21], 0, v[72:73]
	v_lshlrev_b32_e32 v64, 1, v64
	v_lshl_add_u64 v[72:73], v[72:73], 0, v[64:65]
	v_lshrrev_b32_e32 v64, 1, v234
	v_and_b32_e32 v64, 16, v64
	v_lshl_add_u64 v[72:73], v[72:73], 0, v[64:65]
	v_permlane16_swap_b32_e32 v202, v218
	v_permlane16_swap_b32_e32 v203, v219
	v_permlane16_swap_b32_e32 v204, v220
	v_permlane16_swap_b32_e32 v205, v221
	v_add_co_u32_e32 v82, vcc, s62, v72
	v_cvt_pk_bf16_f32 v130, v202, v203
	v_cvt_pk_bf16_f32 v131, v204, v205
	v_cvt_pk_bf16_f32 v132, v218, v219
	v_cvt_pk_bf16_f32 v133, v220, v221
	v_permlane16_swap_b32_e32 v230, v78
	v_permlane16_swap_b32_e32 v231, v79
	v_permlane16_swap_b32_e32 v118, v126
	v_permlane16_swap_b32_e32 v119, v127
	v_addc_co_u32_e32 v83, vcc, 0, v73, vcc
	global_store_dwordx4 v[72:73], v[130:133], off
	v_permlane16_swap_b32_e32 v232, v80
	v_permlane16_swap_b32_e32 v233, v81
	v_cvt_pk_bf16_f32 v132, v78, v79
	v_permlane16_swap_b32_e32 v120, v128
	v_permlane16_swap_b32_e32 v121, v129
	v_cvt_pk_bf16_f32 v78, v118, v119
	v_add_co_u32_e32 v118, vcc, s61, v72
	v_permlane16_swap_b32_e32 v74, v114
	v_permlane16_swap_b32_e32 v75, v115
	v_permlane16_swap_b32_e32 v76, v116
	v_permlane16_swap_b32_e32 v77, v117
	v_cvt_pk_bf16_f32 v133, v80, v81
	v_cvt_pk_bf16_f32 v79, v120, v121
	v_cvt_pk_bf16_f32 v80, v126, v127
	v_cvt_pk_bf16_f32 v81, v128, v129
	v_permlane16_swap_b32_e32 v138, v146
	v_permlane16_swap_b32_e32 v139, v147
	v_permlane16_swap_b32_e32 v140, v148
	v_permlane16_swap_b32_e32 v141, v149
	v_addc_co_u32_e32 v119, vcc, 0, v73, vcc
	v_cvt_pk_bf16_f32 v74, v74, v75
	v_cvt_pk_bf16_f32 v75, v76, v77
	v_cvt_pk_bf16_f32 v76, v114, v115
	v_cvt_pk_bf16_f32 v77, v116, v117
	v_permlane16_swap_b32_e32 v122, v134
	v_permlane16_swap_b32_e32 v123, v135
	v_permlane16_swap_b32_e32 v124, v136
	v_permlane16_swap_b32_e32 v125, v137
	v_permlane16_swap_b32_e32 v26, v30
	v_permlane16_swap_b32_e32 v27, v31
	v_permlane16_swap_b32_e32 v28, v32
	v_permlane16_swap_b32_e32 v29, v33
	global_store_dwordx4 v[72:73], v[78:81], off offset:128
	v_permlane16_swap_b32_e32 v214, v222
	s_nop 0
	v_cvt_pk_bf16_f32 v78, v138, v139
	v_cvt_pk_bf16_f32 v79, v140, v141
	v_cvt_pk_bf16_f32 v80, v146, v147
	v_cvt_pk_bf16_f32 v81, v148, v149
	v_permlane16_swap_b32_e32 v215, v223
	v_permlane16_swap_b32_e32 v216, v224
	v_permlane16_swap_b32_e32 v217, v225
	global_store_dwordx4 v[82:83], v[74:77], off offset:64
	v_permlane16_swap_b32_e32 v142, v150
	s_nop 0
	v_cvt_pk_bf16_f32 v74, v122, v123
	v_cvt_pk_bf16_f32 v75, v124, v125
	v_cvt_pk_bf16_f32 v76, v134, v135
	v_cvt_pk_bf16_f32 v77, v136, v137
	v_permlane16_swap_b32_e32 v143, v151
	v_permlane16_swap_b32_e32 v144, v152
	v_permlane16_swap_b32_e32 v145, v153
	v_permlane16_swap_b32_e32 v58, v226
	v_permlane16_swap_b32_e32 v59, v227
	v_permlane16_swap_b32_e32 v60, v228
	v_permlane16_swap_b32_e32 v61, v229
	v_permlane16_swap_b32_e32 v50, v54
	v_permlane16_swap_b32_e32 v51, v55
	v_permlane16_swap_b32_e32 v52, v56
	v_permlane16_swap_b32_e32 v53, v57
	v_permlane16_swap_b32_e32 v42, v46
	v_permlane16_swap_b32_e32 v43, v47
	v_permlane16_swap_b32_e32 v44, v48
	v_permlane16_swap_b32_e32 v45, v49
	v_permlane16_swap_b32_e32 v34, v38
	v_permlane16_swap_b32_e32 v35, v39
	v_permlane16_swap_b32_e32 v36, v40
	v_permlane16_swap_b32_e32 v37, v41
	v_cvt_pk_bf16_f32 v26, v26, v27
	v_cvt_pk_bf16_f32 v27, v28, v29
	v_cvt_pk_bf16_f32 v28, v30, v31
	v_add_co_u32_e32 v30, vcc, s63, v72
	v_permlane16_swap_b32_e32 v18, v22
	v_permlane16_swap_b32_e32 v19, v23
	v_permlane16_swap_b32_e32 v20, v24
	v_permlane16_swap_b32_e32 v21, v25
	v_permlane16_swap_b32_e32 v10, v14
	v_permlane16_swap_b32_e32 v11, v15
	v_permlane16_swap_b32_e32 v12, v16
	v_permlane16_swap_b32_e32 v13, v17
	v_permlane16_swap_b32_e32 v2, v6
	v_permlane16_swap_b32_e32 v3, v7
	v_permlane16_swap_b32_e32 v4, v8
	v_permlane16_swap_b32_e32 v5, v9
	s_add_i32 s44, s44, s52
	v_cvt_pk_bf16_f32 v130, v230, v231
	v_cvt_pk_bf16_f32 v131, v232, v233
	global_store_dwordx4 v[72:73], v[78:81], off offset:192
	global_store_dwordx4 v[82:83], v[74:77], off offset:128
	v_cvt_pk_bf16_f32 v58, v58, v59
	v_cvt_pk_bf16_f32 v78, v214, v215
	v_cvt_pk_bf16_f32 v79, v216, v217
	v_cvt_pk_bf16_f32 v80, v222, v223
	v_cvt_pk_bf16_f32 v81, v224, v225
	v_cvt_pk_bf16_f32 v74, v142, v143
	v_cvt_pk_bf16_f32 v75, v144, v145
	v_cvt_pk_bf16_f32 v76, v150, v151
	v_cvt_pk_bf16_f32 v77, v152, v153
	v_cvt_pk_bf16_f32 v59, v60, v61
	v_cvt_pk_bf16_f32 v60, v226, v227
	v_cvt_pk_bf16_f32 v61, v228, v229
	v_cvt_pk_bf16_f32 v50, v50, v51
	v_cvt_pk_bf16_f32 v51, v52, v53
	v_cvt_pk_bf16_f32 v52, v54, v55
	v_cvt_pk_bf16_f32 v53, v56, v57
	v_cvt_pk_bf16_f32 v42, v42, v43
	v_cvt_pk_bf16_f32 v43, v44, v45
	v_cvt_pk_bf16_f32 v44, v46, v47
	v_cvt_pk_bf16_f32 v45, v48, v49
	v_cvt_pk_bf16_f32 v34, v34, v35
	v_cvt_pk_bf16_f32 v35, v36, v37
	v_cvt_pk_bf16_f32 v36, v38, v39
	v_cvt_pk_bf16_f32 v37, v40, v41
	v_cvt_pk_bf16_f32 v29, v32, v33
	v_addc_co_u32_e32 v31, vcc, 0, v73, vcc
	v_cvt_pk_bf16_f32 v18, v18, v19
	v_cvt_pk_bf16_f32 v19, v20, v21
	v_cvt_pk_bf16_f32 v20, v22, v23
	v_cvt_pk_bf16_f32 v21, v24, v25
	v_cvt_pk_bf16_f32 v10, v10, v11
	v_cvt_pk_bf16_f32 v11, v12, v13
	v_cvt_pk_bf16_f32 v12, v14, v15
	v_cvt_pk_bf16_f32 v13, v16, v17
	v_cvt_pk_bf16_f32 v2, v2, v3
	v_cvt_pk_bf16_f32 v3, v4, v5
	v_cvt_pk_bf16_f32 v4, v6, v7
	v_cvt_pk_bf16_f32 v5, v8, v9
	s_cmpk_lt_i32 s44, 0x100
	global_store_dwordx4 v[72:73], v[130:133], off offset:64
	global_store_dwordx4 v[118:119], v[78:81], off offset:-4096
	global_store_dwordx4 v[82:83], v[74:77], off offset:192
	global_store_dwordx4 v[118:119], v[58:61], off
	global_store_dwordx4 v[118:119], v[50:53], off offset:64
	global_store_dwordx4 v[118:119], v[42:45], off offset:128
	global_store_dwordx4 v[118:119], v[34:37], off offset:192
	global_store_dwordx4 v[30:31], v[26:29], off
	global_store_dwordx4 v[30:31], v[18:21], off offset:64
	global_store_dwordx4 v[30:31], v[10:13], off offset:128
	global_store_dwordx4 v[30:31], v[2:5], off offset:192
	s_cbranch_scc0 .LBB0_279

.LBB0_270:
	s_xor_b64 s[74:75], s[48:49], -1
	s_mov_b64 s[50:51], 0x200
	s_mov_b64 s[48:49], 0
	s_and_b64 vcc, exec, s[74:75]
	s_cbranch_vccnz .LBB0_277
	s_lshl_b32 s98, s46, 3
	s_ashr_i32 s99, s98, 31
	s_lshl_b64 s[98:99], s[98:99], 11
	s_lshl_b32 s100, s45, 9
	s_add_u32 s100, s100, s59
	s_addc_u32 s101, 0, s60
	s_add_u32 s100, s100, s98
	s_addc_u32 s101, s101, s99
	v_and_b32_e32 v228, 15, v62
	v_or_b32_e32 v228, s100, v228
	v_mov_b32_e32 v229, s101
	v_bfe_u32 v230, v62, 4, 2
	v_lshlrev_b64 v[228:229], 6, v[228:229]
	v_lshlrev_b32_e32 v230, 4, v230
	v_mov_b32_e32 v231, 0
	v_lshl_add_u64 v[228:229], s[12:13], 0, v[228:229]
	v_lshl_add_u64 v[228:229], v[228:229], 0, v[230:231]
	global_load_dwordx4 v[236:239], v[228:229], off
	global_load_dwordx4 v[240:243], v[228:229], off offset:1024
	global_load_dwordx4 v[244:247], v[228:229], off offset:2048
	global_load_dwordx4 v[248:251], v[228:229], off offset:3072
